# MLP-in GEMM: next row tile's row-statistics prep moved out of the main loop (no mid-loop vmcnt(0) drain) into the epilogue start, loads issued with the column-info loads
# baseline (speedup 1.0000x reference)
;     __device__ __forceinline__ void prep(int pm, int par, LAS unsigned char* lds) const { if (fold) prep_rowstats(stat, pm, par, lds); }
;     __device__ __forceinline__ void prep(int pm, int par, LAS unsigned char* lds) const { if (!ident) prep_rowstats(stat, pm, par, lds); }
;     __device__ __forceinline__ void prep(int pm, int par, LAS unsigned char* lds) const { prep_rowstats(stat, pm, par, lds); }
; #define G_STAGE(bufoff, gbase) do { _Pragma("unroll") for (int _i = 0; _i < 2; ++_i) \
;         __builtin_amdgcn_global_load_lds((const unsigned*)((const char*)(gbase) + voff[_i]), (LAS unsigned*)(lds + (bufoff) + ldsw + _i * 8192), 16, 0, 0); } while (0)
; template <class Epi>
; __device__ __forceinline__ void gemm_phase(LAS unsigned char* lds, const bf16_t* Ag, const bf16_t* Btg, const int K, const int nM, const int nN, const Epi& E) {
;     ...
;         for (int t = 0; t < nt; t += 2) {
;             const bool last = (t == nt - 2);
;             const char* a1 = cA + (size_t)(t + 1) * kstep;
;             const char* a2 = last ? nA : cA + (size_t)(t + 2) * kstep; const char* b2 = last ? nB : cB + (size_t)(t + 2) * kstep;
;             const char* a3 = a2 + kstep; const char* b3 = b2 + kstep;
;             if (last && has_next && pmn != pm) E.prep(pmn, par ^ 1, lds);
;             G_LDB(B0, 0, 0); G_SCHED; G_LDA(At, 0, 0); G_STAGE(G_SA(1, 1), a1 + hstep);
;             G_WAIT_L(8); G_BAR; G_WAIT_L(0); G_MMA(0, 0, At, B0); G_BAR; G_SCHED;
;             G_LDB(B1, 0, 1); G_STAGE(G_SB(0, 0), b2);
;             G_BAR; G_WAIT_L(0); G_MMA(0, 1, At, B1); G_BAR;
;             G_LDA(At, 0, 1); G_STAGE(G_SA(0, 0), a2);
;             G_BAR; G_WAIT_L(0); G_MMA(1, 0, At, B0); G_BAR; G_SCHED;
;             G_STAGE(G_SB(0, 1), b2 + hstep);
;             G_WAIT_V(6); G_BAR; G_MMA(1, 1, At, B1); G_BAR;
;             G_LDB(B0, 1, 0); G_SCHED; G_LDA(At, 1, 0); G_STAGE(G_SA(0, 1), a2 + hstep);
;             G_WAIT_L(8); G_BAR; G_WAIT_L(0); G_MMA(0, 0, At, B0); G_BAR; G_SCHED;
;     ...
; #pragma unroll
;         for (int a = 0; a < 2; ++a)
; #pragma unroll
;             for (int b = 0; b < 2; ++b)
; #pragma unroll
;                 for (int m = 0; m < 4; ++m)
; #pragma unroll
;                     for (int n = 0; n < 2; ++n) acc[a][b][m][n] = (f32x4){0.f, 0.f, 0.f, 0.f};
;         if (pmn != pm) par ^= 1;
;         u = un; pm = pmn; pn = pnn; cA = nA; cB = nB;
.LBB0_76:
	s_ashr_i32 s47, s12, 6
	s_and_b64 s[14:15], s[48:49], exec
	s_cselect_b32 s14, s68, s47
	s_ashr_i32 s15, s14, 31
	s_lshl_b64 s[14:15], s[14:15], 19
	s_add_u32 s44, s24, s14
	s_addc_u32 s45, s25, s15
	s_and_b64 s[14:15], s[48:49], exec
	s_cselect_b32 s15, s53, s45
	s_cselect_b32 s69, s52, s44
	s_cmp_eq_u32 s67, s66
	s_cselect_b64 s[54:55], -1, 0
	s_lshl_b32 s14, s64, 11
	s_xor_b32 s12, s14, 0x800
	s_add_i32 s70, s12, 0
	s_add_i32 s70, s70, 0x20000
	s_or_b64 s[48:49], s[48:49], s[54:55]
	s_add_u32 s71, s52, 0x100
	s_addc_u32 s72, s53, 0
	s_add_u32 s50, s50, 0x40080
	v_mov_b32_e32 v8, 0
	s_addc_u32 s51, s51, 0
	s_mov_b32 s73, -2
	v_mov_b32_e32 v9, v8
	v_mov_b32_e32 v10, v8
	v_mov_b32_e32 v11, v8
	v_mov_b32_e32 v12, v8
	v_mov_b32_e32 v13, v8
	v_mov_b32_e32 v14, v8
	v_mov_b32_e32 v15, v8
	v_mov_b32_e32 v24, v8
	v_mov_b32_e32 v25, v8
	v_mov_b32_e32 v26, v8
	v_mov_b32_e32 v27, v8
	v_mov_b32_e32 v28, v8
	v_mov_b32_e32 v29, v8
	v_mov_b32_e32 v30, v8
	v_mov_b32_e32 v31, v8
	v_mov_b32_e32 v40, v8
	v_mov_b32_e32 v41, v8
	v_mov_b32_e32 v42, v8
	v_mov_b32_e32 v43, v8
	v_mov_b32_e32 v44, v8
	v_mov_b32_e32 v45, v8
	v_mov_b32_e32 v46, v8
	v_mov_b32_e32 v47, v8
	v_mov_b32_e32 v56, v8
	v_mov_b32_e32 v57, v8
	v_mov_b32_e32 v58, v8
	v_mov_b32_e32 v59, v8
	v_mov_b32_e32 v60, v8
	v_mov_b32_e32 v61, v8
	v_mov_b32_e32 v62, v8
	v_mov_b32_e32 v63, v8
	v_mov_b32_e32 v72, v8
	v_mov_b32_e32 v73, v8
	v_mov_b32_e32 v74, v8
	v_mov_b32_e32 v75, v8
	v_mov_b32_e32 v76, v8
	v_mov_b32_e32 v77, v8
	v_mov_b32_e32 v78, v8
	v_mov_b32_e32 v79, v8
	v_mov_b32_e32 v88, v8
	v_mov_b32_e32 v89, v8
	v_mov_b32_e32 v90, v8
	v_mov_b32_e32 v91, v8
	v_mov_b32_e32 v92, v8
	v_mov_b32_e32 v93, v8
	v_mov_b32_e32 v94, v8
	v_mov_b32_e32 v95, v8
	v_mov_b32_e32 v104, v8
	v_mov_b32_e32 v105, v8
	v_mov_b32_e32 v106, v8
	v_mov_b32_e32 v107, v8
	v_mov_b32_e32 v108, v8
	v_mov_b32_e32 v109, v8
	v_mov_b32_e32 v110, v8
	v_mov_b32_e32 v111, v8
	v_mov_b32_e32 v120, v8
	v_mov_b32_e32 v121, v8
	v_mov_b32_e32 v122, v8
	v_mov_b32_e32 v123, v8
	v_mov_b32_e32 v144, v8
	v_mov_b32_e32 v145, v8
	v_mov_b32_e32 v146, v8
	v_mov_b32_e32 v147, v8
	v_mov_b32_e32 v80, v8
	v_mov_b32_e32 v81, v8
	v_mov_b32_e32 v82, v8
	v_mov_b32_e32 v83, v8
	v_mov_b32_e32 v84, v8
	v_mov_b32_e32 v85, v8
	v_mov_b32_e32 v86, v8
	v_mov_b32_e32 v87, v8
	v_mov_b32_e32 v96, v8
	v_mov_b32_e32 v97, v8
	v_mov_b32_e32 v98, v8
	v_mov_b32_e32 v99, v8
	v_mov_b32_e32 v100, v8
	v_mov_b32_e32 v101, v8
	v_mov_b32_e32 v102, v8
	v_mov_b32_e32 v103, v8
	v_mov_b32_e32 v112, v8
	v_mov_b32_e32 v113, v8
	v_mov_b32_e32 v114, v8
	v_mov_b32_e32 v115, v8
	v_mov_b32_e32 v116, v8
	v_mov_b32_e32 v117, v8
	v_mov_b32_e32 v118, v8
	v_mov_b32_e32 v119, v8
	v_mov_b32_e32 v160, v8
	v_mov_b32_e32 v161, v8
	v_mov_b32_e32 v162, v8
	v_mov_b32_e32 v163, v8
	v_mov_b32_e32 v164, v8
	v_mov_b32_e32 v165, v8
	v_mov_b32_e32 v166, v8
	v_mov_b32_e32 v167, v8
	v_mov_b32_e32 v68, v8
	v_mov_b32_e32 v69, v8
	v_mov_b32_e32 v70, v8
	v_mov_b32_e32 v71, v8
	v_mov_b32_e32 v64, v8
	v_mov_b32_e32 v65, v8
	v_mov_b32_e32 v66, v8
	v_mov_b32_e32 v67, v8
	v_mov_b32_e32 v52, v8
	v_mov_b32_e32 v53, v8
	v_mov_b32_e32 v54, v8
	v_mov_b32_e32 v55, v8
	v_mov_b32_e32 v48, v8
	v_mov_b32_e32 v49, v8
	v_mov_b32_e32 v50, v8
	v_mov_b32_e32 v51, v8
	v_mov_b32_e32 v36, v8
	v_mov_b32_e32 v37, v8
	v_mov_b32_e32 v38, v8
	v_mov_b32_e32 v39, v8
	v_mov_b32_e32 v32, v8
	v_mov_b32_e32 v33, v8
	v_mov_b32_e32 v34, v8
	v_mov_b32_e32 v35, v8
	v_mov_b32_e32 v20, v8
	v_mov_b32_e32 v21, v8
	v_mov_b32_e32 v22, v8
	v_mov_b32_e32 v23, v8
	v_mov_b32_e32 v16, v8
	v_mov_b32_e32 v17, v8
	v_mov_b32_e32 v18, v8
	v_mov_b32_e32 v19, v8
	s_branch .LBB0_79
.LBB0_78:
	s_add_u32 s12, s50, 0xfffc0080
	s_addc_u32 s26, s51, -1
	s_and_b64 s[52:53], s[52:53], exec
	s_cselect_b32 s55, s26, s43
	s_cselect_b32 s54, s12, s42
	s_cselect_b32 s53, s72, s15
	s_cselect_b32 s52, s71, s69
	s_add_i32 s12, 0, 0x10000
	v_add_u32_e32 v136, s12, v175
	ds_read_b128 v[124:127], v136
	ds_read_b128 v[128:131], v136 offset:1024
	ds_read_b128 v[132:135], v136 offset:2048
	ds_read_b128 v[136:139], v136 offset:3072
	v_lshl_add_u64 v[172:173], s[50:51], 0, v[170:171]
	s_add_i32 m0, s58, 0xc000
	ds_read_b128 v[140:143], v186
	ds_read_b128 v[148:151], v186 offset:1024
	ds_read_b128 v[152:155], v186 offset:2048
	ds_read_b128 v[156:159], v186 offset:3072
	ds_read_b128 v[188:191], v186 offset:4096
	ds_read_b128 v[192:195], v186 offset:5120
	ds_read_b128 v[222:225], v186 offset:6144
	ds_read_b128 v[226:229], v186 offset:7168
	global_load_lds_dwordx4 v[172:173], off
	v_lshl_add_u64 v[172:173], s[50:51], 0, v[168:169]
	s_add_i32 m0, s58, 0xe000
	s_nop 0
	global_load_lds_dwordx4 v[172:173], off
	s_waitcnt lgkmcnt(8)
	s_barrier
	s_waitcnt lgkmcnt(0)
	s_setprio 1
	s_waitcnt lgkmcnt(0)
	v_mfma_f32_16x16x32_bf16 v[164:167], v[124:127], v[140:143], v[164:167]
	v_mfma_f32_16x16x32_bf16 v[160:163], v[132:135], v[140:143], v[160:163]
	v_mfma_f32_16x16x32_bf16 v[116:119], v[124:127], v[152:155], v[116:119]
	v_mfma_f32_16x16x32_bf16 v[112:115], v[132:135], v[152:155], v[112:115]
	v_mfma_f32_16x16x32_bf16 v[100:103], v[124:127], v[188:191], v[100:103]
	v_mfma_f32_16x16x32_bf16 v[96:99], v[132:135], v[188:191], v[96:99]
	v_mfma_f32_16x16x32_bf16 v[84:87], v[124:127], v[222:225], v[84:87]
	v_mfma_f32_16x16x32_bf16 v[80:83], v[132:135], v[222:225], v[80:83]
	v_mfma_f32_16x16x32_bf16 v[164:167], v[128:131], v[148:151], v[164:167]
	v_mfma_f32_16x16x32_bf16 v[160:163], v[136:139], v[148:151], v[160:163]
	v_mfma_f32_16x16x32_bf16 v[116:119], v[128:131], v[156:159], v[116:119]
	v_mfma_f32_16x16x32_bf16 v[112:115], v[136:139], v[156:159], v[112:115]
	v_mfma_f32_16x16x32_bf16 v[100:103], v[128:131], v[192:195], v[100:103]
	v_mfma_f32_16x16x32_bf16 v[96:99], v[136:139], v[192:195], v[96:99]
	v_mfma_f32_16x16x32_bf16 v[84:87], v[128:131], v[226:229], v[84:87]
	v_mfma_f32_16x16x32_bf16 v[80:83], v[136:139], v[226:229], v[80:83]
	s_setprio 0
	s_barrier
; #define G_STAGE(bufoff, gbase) do { _Pragma("unroll") for (int _i = 0; _i < 2; ++_i) \
;         __builtin_amdgcn_global_load_lds((const unsigned*)((const char*)(gbase) + voff[_i]), (LAS unsigned*)(lds + (bufoff) + ldsw + _i * 8192), 16, 0, 0); } while (0)
; #define G_LDA(dst, b, h) do { _Pragma("unroll") for (int m = 0; m < 4; ++m) _Pragma("unroll") for (int k = 0; k < 2; ++k) dst[m][k] = *(const LAS bf16x8*)(lds + G_SA(b, h) + aoff + m * 2048 + k * 1024); } while (0)
; #define G_LDB(dst, b, h) do { _Pragma("unroll") for (int n = 0; n < 2; ++n) _Pragma("unroll") for (int k = 0; k < 2; ++k) dst[n][k] = *(const LAS bf16x8*)(lds + G_SB(b, h) + boff + n * 2048 + k * 1024); } while (0)
; #define G_MMA(ai, bj, At, Bt) do { __builtin_amdgcn_s_setprio(1); _Pragma("unroll") for (int m = 0; m < 4; ++m) _Pragma("unroll") for (int n = 0; n < 2; ++n) _Pragma("unroll") for (int k = 0; k < 2; ++k) \
;         acc[ai][bj][m][n] = MFMA16(Bt[n][k], At[m][k], acc[ai][bj][m][n]); __builtin_amdgcn_s_setprio(0); } while (0)
; #define G_WAIT_V(n) asm volatile("s_waitcnt vmcnt(" #n ")" ::: "memory")
; #define G_WAIT_L(n) asm volatile("s_waitcnt lgkmcnt(" #n ")" ::: "memory")
; #define G_BAR __builtin_amdgcn_s_barrier()
; #define G_SCHED __builtin_amdgcn_sched_barrier(0)
; template <class Epi>
; __device__ __forceinline__ void gemm_phase(LAS unsigned char* lds, const bf16_t* Ag, const bf16_t* Btg, const int K, const int nM, const int nN, const Epi& E) {
;     ...
;             G_LDB(B1, 0, 1); G_STAGE(G_SB(0, 0), b2);
;             G_BAR; G_WAIT_L(0); G_MMA(0, 1, At, B1); G_BAR;
;             G_LDA(At, 0, 1); G_STAGE(G_SA(0, 0), a2);
;             G_BAR; G_WAIT_L(0); G_MMA(1, 0, At, B0); G_BAR; G_SCHED;
;             G_STAGE(G_SB(0, 1), b2 + hstep);
;             G_WAIT_V(6); G_BAR; G_MMA(1, 1, At, B1); G_BAR;
;             G_LDB(B0, 1, 0); G_SCHED; G_LDA(At, 1, 0); G_STAGE(G_SA(0, 1), a2 + hstep);
;             G_WAIT_L(8); G_BAR; G_WAIT_L(0); G_MMA(0, 0, At, B0); G_BAR; G_SCHED;
;             G_LDB(B1, 1, 1); G_STAGE(G_SB(1, 0), b3);
;             G_BAR; G_WAIT_L(0); G_MMA(0, 1, At, B1); G_BAR;
;             G_LDA(At, 1, 1); G_STAGE(G_SA(1, 0), a3);
	s_add_i32 s26, 0, 0x14000
	v_add_u32_e32 v172, s26, v175
	s_add_i32 s12, s12, s57
	ds_read_b128 v[230:233], v172
	ds_read_b128 v[234:237], v172 offset:1024
	ds_read_b128 v[238:241], v172 offset:2048
	ds_read_b128 v[242:245], v172 offset:3072
	v_lshl_add_u64 v[172:173], s[52:53], 0, v[0:1]
	s_mov_b32 m0, s12
	v_lshl_add_u64 v[196:197], s[52:53], 0, v[2:3]
	global_load_lds_dwordx4 v[172:173], off
	s_add_i32 m0, s12, 0x2000
	s_nop 0
	global_load_lds_dwordx4 v[196:197], off
	s_barrier
	s_waitcnt lgkmcnt(0)
	s_setprio 1
	s_waitcnt lgkmcnt(0)
	v_mfma_f32_16x16x32_bf16 v[144:147], v[230:233], v[140:143], v[144:147]
	v_mfma_f32_16x16x32_bf16 v[120:123], v[238:241], v[140:143], v[120:123]
	v_mfma_f32_16x16x32_bf16 v[108:111], v[230:233], v[152:155], v[108:111]
	v_mfma_f32_16x16x32_bf16 v[104:107], v[238:241], v[152:155], v[104:107]
	v_mfma_f32_16x16x32_bf16 v[92:95], v[230:233], v[188:191], v[92:95]
	v_mfma_f32_16x16x32_bf16 v[88:91], v[238:241], v[188:191], v[88:91]
	v_mfma_f32_16x16x32_bf16 v[76:79], v[230:233], v[222:225], v[76:79]
	v_mfma_f32_16x16x32_bf16 v[72:75], v[238:241], v[222:225], v[72:75]
	v_mfma_f32_16x16x32_bf16 v[144:147], v[234:237], v[148:151], v[144:147]
	v_mfma_f32_16x16x32_bf16 v[120:123], v[242:245], v[148:151], v[120:123]
	v_mfma_f32_16x16x32_bf16 v[108:111], v[234:237], v[156:159], v[108:111]
	v_mfma_f32_16x16x32_bf16 v[104:107], v[242:245], v[156:159], v[104:107]
	v_mfma_f32_16x16x32_bf16 v[92:95], v[234:237], v[192:195], v[92:95]
	v_mfma_f32_16x16x32_bf16 v[88:91], v[242:245], v[192:195], v[88:91]
	v_mfma_f32_16x16x32_bf16 v[76:79], v[234:237], v[226:229], v[76:79]
	v_mfma_f32_16x16x32_bf16 v[72:75], v[242:245], v[226:229], v[72:75]
	s_setprio 0
	s_mov_b32 m0, s58
	v_lshl_add_u64 v[210:211], s[54:55], 0, v[0:1]
	s_barrier
	ds_read_b128 v[140:143], v186 offset:16384
	ds_read_b128 v[148:151], v186 offset:17408
	ds_read_b128 v[152:155], v186 offset:18432
	ds_read_b128 v[156:159], v186 offset:19456
	ds_read_b128 v[188:191], v186 offset:20480
	ds_read_b128 v[192:195], v186 offset:21504
	ds_read_b128 v[222:225], v186 offset:22528
	ds_read_b128 v[226:229], v186 offset:23552
	global_load_lds_dwordx4 v[210:211], off
	v_lshl_add_u64 v[216:217], s[54:55], 0, v[2:3]
	s_mov_b32 m0, s59
	s_nop 0
	global_load_lds_dwordx4 v[216:217], off
	s_barrier
	s_waitcnt lgkmcnt(0)
	s_setprio 1
	s_waitcnt lgkmcnt(0)
	v_mfma_f32_16x16x32_bf16 v[60:63], v[124:127], v[140:143], v[60:63]
	v_mfma_f32_16x16x32_bf16 v[56:59], v[132:135], v[140:143], v[56:59]
	v_mfma_f32_16x16x32_bf16 v[44:47], v[124:127], v[152:155], v[44:47]
	v_mfma_f32_16x16x32_bf16 v[40:43], v[132:135], v[152:155], v[40:43]
	v_mfma_f32_16x16x32_bf16 v[28:31], v[124:127], v[188:191], v[28:31]
	v_mfma_f32_16x16x32_bf16 v[24:27], v[132:135], v[188:191], v[24:27]
	v_mfma_f32_16x16x32_bf16 v[12:15], v[124:127], v[222:225], v[12:15]
	v_mfma_f32_16x16x32_bf16 v[8:11], v[132:135], v[222:225], v[8:11]
	v_mfma_f32_16x16x32_bf16 v[60:63], v[128:131], v[148:151], v[60:63]
	v_mfma_f32_16x16x32_bf16 v[56:59], v[136:139], v[148:151], v[56:59]
	v_mfma_f32_16x16x32_bf16 v[44:47], v[128:131], v[156:159], v[44:47]
	v_mfma_f32_16x16x32_bf16 v[40:43], v[136:139], v[156:159], v[40:43]
	v_mfma_f32_16x16x32_bf16 v[28:31], v[128:131], v[192:195], v[28:31]
	v_mfma_f32_16x16x32_bf16 v[24:27], v[136:139], v[192:195], v[24:27]
	v_mfma_f32_16x16x32_bf16 v[12:15], v[128:131], v[226:229], v[12:15]
	v_mfma_f32_16x16x32_bf16 v[8:11], v[136:139], v[226:229], v[8:11]
	s_setprio 0
	s_barrier
	s_add_u32 s74, s52, 0x40000
	s_addc_u32 s75, s53, 0
	s_add_i32 s12, s26, s57
	v_lshl_add_u64 v[124:125], s[74:75], 0, v[0:1]
	s_mov_b32 m0, s12
	s_nop 0
	global_load_lds_dwordx4 v[124:125], off
	v_lshl_add_u64 v[124:125], s[74:75], 0, v[2:3]
	s_add_i32 m0, s12, 0x2000
	s_nop 0
	global_load_lds_dwordx4 v[124:125], off
	s_waitcnt vmcnt(6)
	s_barrier
	s_setprio 1
	v_mfma_f32_16x16x32_bf16 v[68:71], v[230:233], v[140:143], v[68:71]
	v_mfma_f32_16x16x32_bf16 v[64:67], v[238:241], v[140:143], v[64:67]
	v_mfma_f32_16x16x32_bf16 v[52:55], v[230:233], v[152:155], v[52:55]
	v_mfma_f32_16x16x32_bf16 v[48:51], v[238:241], v[152:155], v[48:51]
	v_mfma_f32_16x16x32_bf16 v[36:39], v[230:233], v[188:191], v[36:39]
	v_mfma_f32_16x16x32_bf16 v[32:35], v[238:241], v[188:191], v[32:35]
	v_mfma_f32_16x16x32_bf16 v[20:23], v[230:233], v[222:225], v[20:23]
	v_mfma_f32_16x16x32_bf16 v[16:19], v[238:241], v[222:225], v[16:19]
	v_mfma_f32_16x16x32_bf16 v[68:71], v[234:237], v[148:151], v[68:71]
	v_mfma_f32_16x16x32_bf16 v[64:67], v[242:245], v[148:151], v[64:67]
	v_mfma_f32_16x16x32_bf16 v[52:55], v[234:237], v[156:159], v[52:55]
	v_mfma_f32_16x16x32_bf16 v[48:51], v[242:245], v[156:159], v[48:51]
	v_mfma_f32_16x16x32_bf16 v[36:39], v[234:237], v[192:195], v[36:39]
	v_mfma_f32_16x16x32_bf16 v[32:35], v[242:245], v[192:195], v[32:35]
	v_mfma_f32_16x16x32_bf16 v[20:23], v[234:237], v[226:229], v[20:23]
	v_mfma_f32_16x16x32_bf16 v[16:19], v[242:245], v[226:229], v[16:19]
	s_setprio 0
	s_add_i32 s12, 0, 0x18000
	v_add_u32_e32 v136, s12, v175
	s_barrier
	ds_read_b128 v[124:127], v136
	ds_read_b128 v[128:131], v136 offset:1024
	ds_read_b128 v[132:135], v136 offset:2048
	ds_read_b128 v[136:139], v136 offset:3072
	s_add_u32 s54, s54, 0x40000
	s_addc_u32 s55, s55, 0
	s_mov_b32 m0, s60
	v_lshl_add_u64 v[230:231], s[54:55], 0, v[0:1]
	ds_read_b128 v[140:143], v186 offset:32768
	ds_read_b128 v[148:151], v186 offset:33792
	ds_read_b128 v[152:155], v186 offset:34816
	ds_read_b128 v[156:159], v186 offset:35840
	ds_read_b128 v[188:191], v186 offset:36864
	ds_read_b128 v[192:195], v186 offset:37888
	ds_read_b128 v[222:225], v186 offset:38912
	ds_read_b128 v[226:229], v186 offset:39936
	global_load_lds_dwordx4 v[230:231], off
	v_lshl_add_u64 v[230:231], s[54:55], 0, v[2:3]
	s_mov_b32 m0, s61
	s_nop 0
	global_load_lds_dwordx4 v[230:231], off
	s_waitcnt lgkmcnt(8)
	s_barrier
; #define G_STAGE(bufoff, gbase) do { _Pragma("unroll") for (int _i = 0; _i < 2; ++_i) \
;         __builtin_amdgcn_global_load_lds((const unsigned*)((const char*)(gbase) + voff[_i]), (LAS unsigned*)(lds + (bufoff) + ldsw + _i * 8192), 16, 0, 0); } while (0)
; #define G_LDA(dst, b, h) do { _Pragma("unroll") for (int m = 0; m < 4; ++m) _Pragma("unroll") for (int k = 0; k < 2; ++k) dst[m][k] = *(const LAS bf16x8*)(lds + G_SA(b, h) + aoff + m * 2048 + k * 1024); } while (0)
; #define G_LDB(dst, b, h) do { _Pragma("unroll") for (int n = 0; n < 2; ++n) _Pragma("unroll") for (int k = 0; k < 2; ++k) dst[n][k] = *(const LAS bf16x8*)(lds + G_SB(b, h) + boff + n * 2048 + k * 1024); } while (0)
; #define G_MMA(ai, bj, At, Bt) do { __builtin_amdgcn_s_setprio(1); _Pragma("unroll") for (int m = 0; m < 4; ++m) _Pragma("unroll") for (int n = 0; n < 2; ++n) _Pragma("unroll") for (int k = 0; k < 2; ++k) \
;         acc[ai][bj][m][n] = MFMA16(Bt[n][k], At[m][k], acc[ai][bj][m][n]); __builtin_amdgcn_s_setprio(0); } while (0)
; #define G_WAIT_V(n) asm volatile("s_waitcnt vmcnt(" #n ")" ::: "memory")
; #define G_WAIT_L(n) asm volatile("s_waitcnt lgkmcnt(" #n ")" ::: "memory")
; #define G_BAR __builtin_amdgcn_s_barrier()
; #define G_SCHED __builtin_amdgcn_sched_barrier(0)
; template <class Epi>
; __device__ __forceinline__ void gemm_phase(LAS unsigned char* lds, const bf16_t* Ag, const bf16_t* Btg, const int K, const int nM, const int nN, const Epi& E) {
;     ...
;             G_LDB(B0, 1, 0); G_SCHED; G_LDA(At, 1, 0); G_STAGE(G_SA(0, 1), a2 + hstep);
;             G_WAIT_L(8); G_BAR; G_WAIT_L(0); G_MMA(0, 0, At, B0); G_BAR; G_SCHED;
;             G_LDB(B1, 1, 1); G_STAGE(G_SB(1, 0), b3);
;             G_BAR; G_WAIT_L(0); G_MMA(0, 1, At, B1); G_BAR;
;             G_LDA(At, 1, 1); G_STAGE(G_SA(1, 0), a3);
;             G_BAR; G_WAIT_L(0); G_MMA(1, 0, At, B0); G_BAR; G_SCHED;
;             G_STAGE(G_SB(1, 1), b3 + hstep);
;             G_WAIT_V(6); G_BAR; G_MMA(1, 1, At, B1); G_BAR;
;         }
	s_waitcnt lgkmcnt(0)
	s_setprio 1
	s_waitcnt lgkmcnt(0)
	v_mfma_f32_16x16x32_bf16 v[164:167], v[124:127], v[140:143], v[164:167]
	v_mfma_f32_16x16x32_bf16 v[160:163], v[132:135], v[140:143], v[160:163]
	v_mfma_f32_16x16x32_bf16 v[116:119], v[124:127], v[152:155], v[116:119]
	v_mfma_f32_16x16x32_bf16 v[112:115], v[132:135], v[152:155], v[112:115]
	v_mfma_f32_16x16x32_bf16 v[100:103], v[124:127], v[188:191], v[100:103]
	v_mfma_f32_16x16x32_bf16 v[96:99], v[132:135], v[188:191], v[96:99]
	v_mfma_f32_16x16x32_bf16 v[84:87], v[124:127], v[222:225], v[84:87]
	v_mfma_f32_16x16x32_bf16 v[80:83], v[132:135], v[222:225], v[80:83]
	v_mfma_f32_16x16x32_bf16 v[164:167], v[128:131], v[148:151], v[164:167]
	v_mfma_f32_16x16x32_bf16 v[160:163], v[136:139], v[148:151], v[160:163]
	v_mfma_f32_16x16x32_bf16 v[116:119], v[128:131], v[156:159], v[116:119]
	v_mfma_f32_16x16x32_bf16 v[112:115], v[136:139], v[156:159], v[112:115]
	v_mfma_f32_16x16x32_bf16 v[100:103], v[128:131], v[192:195], v[100:103]
	v_mfma_f32_16x16x32_bf16 v[96:99], v[136:139], v[192:195], v[96:99]
	v_mfma_f32_16x16x32_bf16 v[84:87], v[128:131], v[226:229], v[84:87]
	v_mfma_f32_16x16x32_bf16 v[80:83], v[136:139], v[226:229], v[80:83]
	s_setprio 0
	s_barrier
	s_add_i32 s26, 0, 0x1c000
	s_add_i32 s12, s12, s57
	v_add_u32_e32 v187, s26, v175
	v_lshl_add_u64 v[172:173], v[172:173], 0, s[94:95]
	s_mov_b32 m0, s12
	ds_read_b128 v[230:233], v187
	ds_read_b128 v[234:237], v187 offset:1024
	ds_read_b128 v[238:241], v187 offset:2048
	ds_read_b128 v[242:245], v187 offset:3072
	global_load_lds_dwordx4 v[172:173], off
	v_lshl_add_u64 v[172:173], v[196:197], 0, s[94:95]
	s_add_i32 m0, s12, 0x2000
	s_nop 0
	global_load_lds_dwordx4 v[172:173], off
	s_barrier
	s_waitcnt lgkmcnt(0)
	s_setprio 1
	s_waitcnt lgkmcnt(0)
	v_mfma_f32_16x16x32_bf16 v[144:147], v[230:233], v[140:143], v[144:147]
	v_mfma_f32_16x16x32_bf16 v[120:123], v[238:241], v[140:143], v[120:123]
	v_mfma_f32_16x16x32_bf16 v[108:111], v[230:233], v[152:155], v[108:111]
	v_mfma_f32_16x16x32_bf16 v[104:107], v[238:241], v[152:155], v[104:107]
	v_mfma_f32_16x16x32_bf16 v[92:95], v[230:233], v[188:191], v[92:95]
	v_mfma_f32_16x16x32_bf16 v[88:91], v[238:241], v[188:191], v[88:91]
	v_mfma_f32_16x16x32_bf16 v[76:79], v[230:233], v[222:225], v[76:79]
	v_mfma_f32_16x16x32_bf16 v[72:75], v[238:241], v[222:225], v[72:75]
	v_mfma_f32_16x16x32_bf16 v[144:147], v[234:237], v[148:151], v[144:147]
	v_mfma_f32_16x16x32_bf16 v[120:123], v[242:245], v[148:151], v[120:123]
	v_mfma_f32_16x16x32_bf16 v[108:111], v[234:237], v[156:159], v[108:111]
	v_mfma_f32_16x16x32_bf16 v[104:107], v[242:245], v[156:159], v[104:107]
	v_mfma_f32_16x16x32_bf16 v[92:95], v[234:237], v[192:195], v[92:95]
	v_mfma_f32_16x16x32_bf16 v[88:91], v[242:245], v[192:195], v[88:91]
	v_mfma_f32_16x16x32_bf16 v[76:79], v[234:237], v[226:229], v[76:79]
	v_mfma_f32_16x16x32_bf16 v[72:75], v[242:245], v[226:229], v[72:75]
	s_setprio 0
	s_mov_b32 m0, s62
	v_lshl_add_u64 v[172:173], v[210:211], 0, s[94:95]
	s_barrier
	ds_read_b128 v[140:143], v186 offset:49152
	ds_read_b128 v[148:151], v186 offset:50176
	ds_read_b128 v[152:155], v186 offset:51200
	ds_read_b128 v[156:159], v186 offset:52224
	ds_read_b128 v[188:191], v186 offset:53248
	ds_read_b128 v[192:195], v186 offset:54272
	ds_read_b128 v[222:225], v186 offset:55296
	ds_read_b128 v[226:229], v186 offset:56320
	global_load_lds_dwordx4 v[172:173], off
	v_lshl_add_u64 v[172:173], v[216:217], 0, s[94:95]
	s_mov_b32 m0, s63
	s_nop 0
	global_load_lds_dwordx4 v[172:173], off
	s_barrier
	s_waitcnt lgkmcnt(0)
	s_setprio 1
	s_waitcnt lgkmcnt(0)
	v_mfma_f32_16x16x32_bf16 v[60:63], v[124:127], v[140:143], v[60:63]
	v_mfma_f32_16x16x32_bf16 v[56:59], v[132:135], v[140:143], v[56:59]
	v_mfma_f32_16x16x32_bf16 v[44:47], v[124:127], v[152:155], v[44:47]
	v_mfma_f32_16x16x32_bf16 v[40:43], v[132:135], v[152:155], v[40:43]
	v_mfma_f32_16x16x32_bf16 v[28:31], v[124:127], v[188:191], v[28:31]
	v_mfma_f32_16x16x32_bf16 v[24:27], v[132:135], v[188:191], v[24:27]
	v_mfma_f32_16x16x32_bf16 v[12:15], v[124:127], v[222:225], v[12:15]
	v_mfma_f32_16x16x32_bf16 v[8:11], v[132:135], v[222:225], v[8:11]
	v_mfma_f32_16x16x32_bf16 v[60:63], v[128:131], v[148:151], v[60:63]
	v_mfma_f32_16x16x32_bf16 v[56:59], v[136:139], v[148:151], v[56:59]
	v_mfma_f32_16x16x32_bf16 v[44:47], v[128:131], v[156:159], v[44:47]
	v_mfma_f32_16x16x32_bf16 v[40:43], v[136:139], v[156:159], v[40:43]
	v_mfma_f32_16x16x32_bf16 v[28:31], v[128:131], v[192:195], v[28:31]
	v_mfma_f32_16x16x32_bf16 v[24:27], v[136:139], v[192:195], v[24:27]
	v_mfma_f32_16x16x32_bf16 v[12:15], v[128:131], v[226:229], v[12:15]
	v_mfma_f32_16x16x32_bf16 v[8:11], v[136:139], v[226:229], v[8:11]
	s_setprio 0
	s_barrier
	s_add_u32 s52, s52, 0x40080
	s_addc_u32 s53, s53, 0
	s_add_i32 s12, s26, s57
	v_lshl_add_u64 v[124:125], s[52:53], 0, v[0:1]
	s_mov_b32 m0, s12
	s_nop 0
	global_load_lds_dwordx4 v[124:125], off
	v_lshl_add_u64 v[124:125], s[52:53], 0, v[2:3]
	s_add_i32 m0, s12, 0x2000
	s_nop 0
	global_load_lds_dwordx4 v[124:125], off
	s_waitcnt vmcnt(6)
	s_barrier
	s_setprio 1
	v_mfma_f32_16x16x32_bf16 v[68:71], v[230:233], v[140:143], v[68:71]
	v_mfma_f32_16x16x32_bf16 v[64:67], v[238:241], v[140:143], v[64:67]
	v_mfma_f32_16x16x32_bf16 v[52:55], v[230:233], v[152:155], v[52:55]
	v_mfma_f32_16x16x32_bf16 v[48:51], v[238:241], v[152:155], v[48:51]
	v_mfma_f32_16x16x32_bf16 v[36:39], v[230:233], v[188:191], v[36:39]
	v_mfma_f32_16x16x32_bf16 v[32:35], v[238:241], v[188:191], v[32:35]
	v_mfma_f32_16x16x32_bf16 v[20:23], v[230:233], v[222:225], v[20:23]
	v_mfma_f32_16x16x32_bf16 v[16:19], v[238:241], v[222:225], v[16:19]
	v_mfma_f32_16x16x32_bf16 v[68:71], v[234:237], v[148:151], v[68:71]
	v_mfma_f32_16x16x32_bf16 v[64:67], v[242:245], v[148:151], v[64:67]
	v_mfma_f32_16x16x32_bf16 v[52:55], v[234:237], v[156:159], v[52:55]
	v_mfma_f32_16x16x32_bf16 v[48:51], v[242:245], v[156:159], v[48:51]
	v_mfma_f32_16x16x32_bf16 v[36:39], v[234:237], v[192:195], v[36:39]
	v_mfma_f32_16x16x32_bf16 v[32:35], v[242:245], v[192:195], v[32:35]
	v_mfma_f32_16x16x32_bf16 v[20:23], v[234:237], v[226:229], v[20:23]
	v_mfma_f32_16x16x32_bf16 v[16:19], v[242:245], v[226:229], v[16:19]
	s_setprio 0
	s_add_i32 s73, s73, 2
	s_add_u32 s71, s71, 0x100
	s_addc_u32 s72, s72, 0
	s_add_u32 s50, s50, 0x100
	s_addc_u32 s51, s51, 0
	s_cmp_gt_u32 s73, 13
	s_barrier
	s_cbranch_scc1 .LBB0_82
; #define LAS __attribute__((address_space(3)))
; __device__ __forceinline__ int tidx() { int t = threadIdx.x; asm volatile("" : "+v"(t)); return t; }
; __device__ __forceinline__ int prow0(int pm) { return (pm >> 4) * LP + PADR + (pm & 15) * 256; }
; __device__ __forceinline__ int trow(int i) { return (i >> 4) * LP + 4144 + (i & 15); }
;     __device__ __forceinline__ void prep(int pm, int par, LAS unsigned char* lds) const { if (fold) prep_rowstats(stat, pm, par, lds); }
;     __device__ __forceinline__ void prep(int pm, int par, LAS unsigned char* lds) const { if (!ident) prep_rowstats(stat, pm, par, lds); }
;     __device__ __forceinline__ void prep(int pm, int par, LAS unsigned char* lds) const { prep_rowstats(stat, pm, par, lds); }
; __device__ __forceinline__ void prep_rowstats(const float* stat, int pm, int par, LAS unsigned char* lds) {
;     const int t = tidx();
;     if (t < (pm < 64 ? 256 : 64)) {
;         const int row = pm < 64 ? prow0(pm) + t : trow(t); const f32x4* sp = (const f32x4*)(stat + (size_t)row * 32);
;         float s1 = 0.f, s2 = 0.f;
; #pragma unroll
;         for (int q = 0; q < 8; ++q) { const f32x4 v = sp[q]; s1 += v[0] + v[2]; s2 += v[1] + v[3]; }
; template <class Epi>
; __device__ __forceinline__ void gemm_phase(LAS unsigned char* lds, const bf16_t* Ag, const bf16_t* Btg, const int K, const int nM, const int nN, const Epi& E) {
;     ...
;         for (int t = 0; t < nt; t += 2) {
;             const bool last = (t == nt - 2);
;             const char* a1 = cA + (size_t)(t + 1) * kstep;
;             const char* a2 = last ? nA : cA + (size_t)(t + 2) * kstep; const char* b2 = last ? nB : cB + (size_t)(t + 2) * kstep;
;             const char* a3 = a2 + kstep; const char* b3 = b2 + kstep;
;             if (last && has_next && pmn != pm) E.prep(pmn, par ^ 1, lds);
.LBB0_79:
	s_cmp_lg_u32 s73, 12
	s_cselect_b64 s[52:53], -1, 0
	s_or_b64 s[54:55], s[48:49], s[52:53]
	s_and_b64 vcc, exec, s[54:55]
	s_branch .LBB0_78
.LBB0_82:
	s_and_b64 vcc, exec, s[48:49]
	s_cbranch_vccnz .Lprep5_a
	v_mov_b32_e32 v250, v198
	s_nop 0
	v_cmp_gt_i32_e32 vcc, s1, v250
	s_and_saveexec_b64 s[54:55], vcc
	s_cbranch_execz .Lprep5_a0
	v_add_u32_e32 v222, s46, v250
	v_ashrrev_i32_e32 v223, 31, v222
	v_lshlrev_b64 v[222:223], 7, v[222:223]
	v_lshl_add_u64 v[196:197], s[18:19], 0, v[222:223]
	global_load_dwordx4 v[222:225], v[196:197], off
	global_load_dwordx4 v[226:229], v[196:197], off offset:16
	global_load_dwordx4 v[230:233], v[196:197], off offset:32
	global_load_dwordx4 v[234:237], v[196:197], off offset:48
	global_load_dwordx4 v[238:241], v[196:197], off offset:64
	global_load_dwordx4 v[242:245], v[196:197], off offset:80
	global_load_dwordx4 v[246:249], v[196:197], off offset:96
	global_load_dwordx4 v[192:195], v[196:197], off offset:112
	v_lshl_add_u32 v250, v250, 3, s70

; #define LAS __attribute__((address_space(3)))
; __device__ __forceinline__ int tidx() { int t = threadIdx.x; asm volatile("" : "+v"(t)); return t; }
; __device__ __forceinline__ int prow0(int pm) { return (pm >> 4) * LP + PADR + (pm & 15) * 256; }
; __device__ __forceinline__ int trow(int i) { return (i >> 4) * LP + 4144 + (i & 15); }
;     __device__ __forceinline__ ColInfo colinfo(int col) const { ColInfo c; c.a = (f32x4){0.f, 0.f, 0.f, 0.f}; c.b = c.a; if (fold) { c.a = *(const f32x4*)(c1 + col); c.b = *(const f32x4*)(c2 + col); } return c; }
; __device__ __forceinline__ void prep_rowstats(const float* stat, int pm, int par, LAS unsigned char* lds) {
;     const int t = tidx();
;     if (t < (pm < 64 ? 256 : 64)) {
;         const int row = pm < 64 ? prow0(pm) + t : trow(t); const f32x4* sp = (const f32x4*)(stat + (size_t)row * 32);
;         float s1 = 0.f, s2 = 0.f;
; #pragma unroll
;         for (int q = 0; q < 8; ++q) { const f32x4 v = sp[q]; s1 += v[0] + v[2]; s2 += v[1] + v[3]; }
;         const float mu = s1 * (1.0f / 1024.0f); const float var = fmaxf(s2 * (1.0f / 1024.0f) - mu * mu, 0.f);
;         ((LAS f32x2*)(lds + RS_OFF + par * 2048))[t] = (f32x2){mu, __builtin_amdgcn_rsqf(var + LN_EPS)};
;     }
; template <class Epi>
; __device__ __forceinline__ void gemm_phase(LAS unsigned char* lds, const bf16_t* Ag, const bf16_t* Btg, const int K, const int nM, const int nN, const Epi& E) {
;     ...
;             ColInfo ci[2][2];
; #pragma unroll
;             for (int bj = 0; bj < 2; ++bj)
; #pragma unroll
;                 for (int n = 0; n < 2; ++n) ci[bj][n] = E.colinfo(pn * 256 + bj * 128 + wc * 32 + n * 16 + fq * 4);
.Lprep5_a:
	v_lshl_or_b32 v188, s68, 8, v185
	v_ashrrev_i32_e32 v189, 31, v188
	v_lshlrev_b64 v[124:125], 2, v[188:189]
	v_lshl_add_u64 v[126:127], s[6:7], 0, v[124:125]
	v_lshl_add_u64 v[124:125], s[22:23], 0, v[124:125]
	global_load_dwordx4 v[148:151], v[126:127], off
	global_load_dwordx4 v[156:159], v[124:125], off
	v_or_b32_e32 v124, 16, v188
	v_ashrrev_i32_e32 v125, 31, v124
	v_lshlrev_b64 v[124:125], 2, v[124:125]
	v_lshl_add_u64 v[126:127], s[6:7], 0, v[124:125]
	v_lshl_add_u64 v[124:125], s[22:23], 0, v[124:125]
	global_load_dwordx4 v[136:139], v[126:127], off
	global_load_dwordx4 v[140:143], v[124:125], off
	v_or_b32_e32 v124, 0x80, v188
	v_ashrrev_i32_e32 v125, 31, v124
	v_lshlrev_b64 v[124:125], 2, v[124:125]
	v_lshl_add_u64 v[126:127], s[6:7], 0, v[124:125]
	v_lshl_add_u64 v[124:125], s[22:23], 0, v[124:125]
	global_load_dwordx4 v[128:131], v[126:127], off
	global_load_dwordx4 v[132:135], v[124:125], off
	v_or_b32_e32 v124, 0x90, v188
	v_ashrrev_i32_e32 v125, 31, v124
	v_lshlrev_b64 v[152:153], 2, v[124:125]
	v_lshl_add_u64 v[124:125], s[6:7], 0, v[152:153]
	global_load_dwordx4 v[124:127], v[124:125], off
	v_lshl_add_u64 v[152:153], s[22:23], 0, v[152:153]
	global_load_dwordx4 v[152:155], v[152:153], off
	s_lshr_b32 s12, s66, 4
	s_lshl_b32 s15, s66, 8
	s_mulk_i32 s12, 0x1040
	s_and_b32 s15, s15, 0xf00
	s_add_i32 s15, s15, s12
	s_add_i32 s12, s14, 0
	s_add_i32 s12, s12, 0x20000
	v_lshl_add_u32 v187, v174, 3, s12
	ds_read_b64 v[172:173], v187
	s_or_b32 s15, s15, 48
	v_add_u32_e32 v190, s15, v174
	v_ashrrev_i32_e32 v191, 31, v190
	v_lshlrev_b64 v[190:191], 13, v[190:191]
	s_waitcnt vmcnt(0)
	s_and_b64 vcc, exec, s[48:49]
	s_cbranch_vccnz .Lprep5_b
	v_cmp_gt_i32_e32 vcc, s1, v198
	s_and_saveexec_b64 s[54:55], vcc
	s_cbranch_execz .Lprep5_b0
	v_pk_add_f32 v[222:223], v[222:223], v[224:225]
	v_pk_add_f32 v[224:225], v[226:227], v[228:229]
	v_pk_add_f32 v[222:223], v[222:223], 0 op_sel_hi:[1,0]
	v_pk_add_f32 v[226:227], v[230:231], v[232:233]
	v_pk_add_f32 v[222:223], v[222:223], v[224:225]
	v_pk_add_f32 v[228:229], v[234:235], v[236:237]
	v_pk_add_f32 v[222:223], v[222:223], v[226:227]
	v_pk_add_f32 v[230:231], v[238:239], v[240:241]
	v_pk_add_f32 v[222:223], v[222:223], v[228:229]
	v_pk_add_f32 v[232:233], v[242:243], v[244:245]
	v_pk_add_f32 v[222:223], v[222:223], v[230:231]
	v_pk_add_f32 v[234:235], v[246:247], v[248:249]
	v_pk_add_f32 v[222:223], v[222:223], v[232:233]
	v_pk_add_f32 v[224:225], v[192:193], v[194:195]
	v_pk_add_f32 v[222:223], v[222:223], v[234:235]
	s_nop 0
	v_pk_add_f32 v[222:223], v[222:223], v[224:225]
	s_nop 0
	v_pk_mul_f32 v[222:223], v[222:223], s[0:1] op_sel_hi:[1,0]
	s_nop 0
	v_fma_f32 v251, -v222, v222, v223
	v_max_f32_e32 v251, 0, v251
	v_add_f32_e32 v251, 0x3727c5ac, v251
	v_rsq_f32_e32 v223, v251
	ds_write_b64 v250, v[222:223]

; __device__ __forceinline__ float bflo(unsigned w) { return __uint_as_float(w << 16); }
; __device__ __forceinline__ float bfhi(unsigned w) { return __uint_as_float(w & 0xffff0000u); }
;     __device__ __forceinline__ void apply(const RowInfo& ri, const ColInfo& ci, int row, int col, f32x4 a, f32x4 pv, float& s1, float& s2) const {
;         f32x4 v = (a - ci.a * ri.mu) * ri.rstd + ci.b;
; #pragma unroll
;         for (int j = 0; j < 4; ++j) { const float r = fmaxf(v[j], 0.f); v[j] = r * r; }
;         *(u32x2*)(hid + (size_t)row * DFF + col) = pack4(v);
; template <class Epi>
; __device__ __forceinline__ void gemm_phase(LAS unsigned char* lds, const bf16_t* Ag, const bf16_t* Btg, const int K, const int nM, const int nN, const Epi& E) {
;     ...
;             for (int gi = 0; gi < 8; ++gi) {
;                 const int ai = gi >> 2, m = gi & 3;
;                 const int lrow = ai * 128 + wr * 64 + m * 16 + fr, row = prow0(pm) + lrow;
;                 if (!Epi::PRELOAD && gi == 0) {
; #pragma unroll
;                     for (int g2 = 0; g2 < 4; ++g2)
; #pragma unroll
;                         for (int bj = 0; bj < 2; ++bj)
; #pragma unroll
;                             for (int n = 0; n < 2; ++n) pk[g2][bj][n] = (u32x2){0u, 0u};
;                 }
;                 if (Epi::PRELOAD && m == 0) {
; #pragma unroll
;                     for (int g2 = 0; g2 < 4; ++g2)
; #pragma unroll
;                         for (int bj = 0; bj < 2; ++bj)
; #pragma unroll
;                             for (int n = 0; n < 2; ++n) pk[g2][bj][n] = E.preload_pk(prow0(pm) + ai * 128 + wr * 64 + g2 * 16 + fr, pn * 256 + bj * 128 + wc * 32 + n * 16 + fq * 4);
;                 }
;                 f32x4 pv[2][2];
; #pragma unroll
;                 for (int bj = 0; bj < 2; ++bj)
; #pragma unroll
;                     for (int n = 0; n < 2; ++n) { const u32x2 w = pk[m][bj][n]; pv[bj][n] = (f32x4){bflo(w.x), bfhi(w.x), bflo(w.y), bfhi(w.y)}; }
;                 const RowInfo ri = E.rowinfo(row, lrow, par, lds);
;                 float s1 = 0.f, s2 = 0.f;
; #pragma unroll
;                 for (int bj = 0; bj < 2; ++bj)
; #pragma unroll
;                     for (int n = 0; n < 2; ++n) E.apply(ri, ci[bj][n], row, pn * 256 + bj * 128 + wc * 32 + n * 16 + fq * 4, acc[ai][bj][m][n], pv[bj][n], s1, s2);
.Lprep5_b:
	s_and_b64 vcc, exec, s[40:41]
	v_xor_b32_e32 v151, 0x80000000, v151
	v_xor_b32_e32 v150, 0x80000000, v150
	s_waitcnt lgkmcnt(0)
	v_pk_fma_f32 v[166:167], v[150:151], v[172:173], v[166:167] op_sel_hi:[1,0,1]
	v_pk_fma_f32 v[164:165], v[148:149], v[172:173], v[164:165] op_sel_hi:[1,0,1] neg_lo:[1,0,0] neg_hi:[1,0,0]
	v_pk_fma_f32 v[166:167], v[172:173], v[166:167], v[158:159] op_sel:[1,0,0]
	v_pk_fma_f32 v[164:165], v[172:173], v[164:165], v[156:157] op_sel:[1,0,0]
	v_max_f32_e32 v166, 0, v166
	v_xor_b32_e32 v139, 0x80000000, v139
	v_xor_b32_e32 v138, 0x80000000, v138
	v_pk_fma_f32 v[162:163], v[138:139], v[172:173], v[162:163] op_sel_hi:[1,0,1]
	v_pk_fma_f32 v[160:161], v[136:137], v[172:173], v[160:161] op_sel_hi:[1,0,1] neg_lo:[1,0,0] neg_hi:[1,0,0]
	v_max_f32_e32 v164, 0, v164
	v_max_f32_e32 v165, 0, v165
	v_max_f32_e32 v167, 0, v167
	v_xor_b32_e32 v131, 0x80000000, v131
	v_xor_b32_e32 v130, 0x80000000, v130
	v_pk_fma_f32 v[146:147], v[130:131], v[172:173], v[146:147] op_sel_hi:[1,0,1]
	v_pk_fma_f32 v[144:145], v[128:129], v[172:173], v[144:145] op_sel_hi:[1,0,1] neg_lo:[1,0,0] neg_hi:[1,0,0]
	v_pk_fma_f32 v[162:163], v[172:173], v[162:163], v[142:143] op_sel:[1,0,0]
	v_pk_fma_f32 v[160:161], v[172:173], v[160:161], v[140:141] op_sel:[1,0,0]
	v_xor_b32_e32 v127, 0x80000000, v127
	v_xor_b32_e32 v126, 0x80000000, v126
	v_pk_fma_f32 v[122:123], v[126:127], v[172:173], v[122:123] op_sel_hi:[1,0,1]
	v_pk_fma_f32 v[120:121], v[124:125], v[172:173], v[120:121] op_sel_hi:[1,0,1] neg_lo:[1,0,0] neg_hi:[1,0,0]
	v_pk_fma_f32 v[146:147], v[172:173], v[146:147], v[134:135] op_sel:[1,0,0]
	v_pk_fma_f32 v[144:145], v[172:173], v[144:145], v[132:133] op_sel:[1,0,0]
	v_pk_fma_f32 v[122:123], v[172:173], v[122:123], v[154:155] op_sel:[1,0,0]
	v_pk_fma_f32 v[120:121], v[172:173], v[120:121], v[152:153] op_sel:[1,0,0]
	v_pk_mul_f32 v[164:165], v[164:165], v[164:165]
	v_pk_mul_f32 v[166:167], v[166:167], v[166:167]
	v_max_f32_e32 v160, 0, v160
	v_max_f32_e32 v161, 0, v161
	v_max_f32_e32 v162, 0, v162
	v_max_f32_e32 v163, 0, v163
	v_max_f32_e32 v144, 0, v144
	v_max_f32_e32 v145, 0, v145
	v_max_f32_e32 v146, 0, v146
	v_max_f32_e32 v147, 0, v147
	v_max_f32_e32 v120, 0, v120
	v_max_f32_e32 v121, 0, v121
	v_max_f32_e32 v122, 0, v122
	v_max_f32_e32 v123, 0, v123
	v_cvt_pk_bf16_f32 v192, v164, v165
	v_cvt_pk_bf16_f32 v193, v166, v167
	v_lshl_add_u64 v[166:167], s[86:87], 0, v[190:191]
	v_lshlrev_b64 v[164:165], 1, v[188:189]
	v_pk_mul_f32 v[160:161], v[160:161], v[160:161]
	v_pk_mul_f32 v[162:163], v[162:163], v[162:163]
	v_pk_mul_f32 v[144:145], v[144:145], v[144:145]
	v_pk_mul_f32 v[146:147], v[146:147], v[146:147]
	v_pk_mul_f32 v[120:121], v[120:121], v[120:121]
	v_pk_mul_f32 v[122:123], v[122:123], v[122:123]
	v_lshl_add_u64 v[166:167], v[166:167], 0, v[164:165]
	v_cvt_pk_bf16_f32 v160, v160, v161
	v_cvt_pk_bf16_f32 v161, v162, v163
	v_cvt_pk_bf16_f32 v144, v144, v145
	v_cvt_pk_bf16_f32 v145, v146, v147
	v_cvt_pk_bf16_f32 v120, v120, v121
	v_cvt_pk_bf16_f32 v121, v122, v123
	global_store_dwordx2 v[166:167], v[192:193], off
	global_store_dwordx2 v[166:167], v[160:161], off offset:32
	global_store_dwordx2 v[166:167], v[144:145], off offset:256
	global_store_dwordx2 v[166:167], v[120:121], off offset:288
	ds_read_b64 v[122:123], v187 offset:128
	v_add_u32_e32 v120, s15, v176
	v_ashrrev_i32_e32 v121, 31, v120
	v_lshlrev_b64 v[120:121], 13, v[120:121]
	s_waitcnt lgkmcnt(0)
	v_pk_fma_f32 v[118:119], v[150:151], v[122:123], v[118:119] op_sel_hi:[1,0,1]
	v_pk_fma_f32 v[116:117], v[148:149], v[122:123], v[116:117] op_sel_hi:[1,0,1] neg_lo:[1,0,0] neg_hi:[1,0,0]
	v_pk_fma_f32 v[118:119], v[122:123], v[118:119], v[158:159] op_sel:[1,0,0]
	v_pk_fma_f32 v[116:117], v[122:123], v[116:117], v[156:157] op_sel:[1,0,0]
	v_pk_fma_f32 v[114:115], v[138:139], v[122:123], v[114:115] op_sel_hi:[1,0,1]
	v_pk_fma_f32 v[112:113], v[136:137], v[122:123], v[112:113] op_sel_hi:[1,0,1] neg_lo:[1,0,0] neg_hi:[1,0,0]
	v_pk_fma_f32 v[110:111], v[130:131], v[122:123], v[110:111] op_sel_hi:[1,0,1]
	v_pk_fma_f32 v[108:109], v[128:129], v[122:123], v[108:109] op_sel_hi:[1,0,1] neg_lo:[1,0,0] neg_hi:[1,0,0]
	v_pk_fma_f32 v[106:107], v[126:127], v[122:123], v[106:107] op_sel_hi:[1,0,1]
	v_pk_fma_f32 v[104:105], v[124:125], v[122:123], v[104:105] op_sel_hi:[1,0,1] neg_lo:[1,0,0] neg_hi:[1,0,0]
	v_max_f32_e32 v116, 0, v116
	v_max_f32_e32 v117, 0, v117
	v_max_f32_e32 v118, 0, v118
	v_max_f32_e32 v119, 0, v119
	v_pk_fma_f32 v[114:115], v[122:123], v[114:115], v[142:143] op_sel:[1,0,0]
	v_pk_fma_f32 v[112:113], v[122:123], v[112:113], v[140:141] op_sel:[1,0,0]
	v_pk_fma_f32 v[110:111], v[122:123], v[110:111], v[134:135] op_sel:[1,0,0]
	v_pk_fma_f32 v[108:109], v[122:123], v[108:109], v[132:133] op_sel:[1,0,0]
	v_pk_fma_f32 v[106:107], v[122:123], v[106:107], v[154:155] op_sel:[1,0,0]
	v_pk_fma_f32 v[104:105], v[122:123], v[104:105], v[152:153] op_sel:[1,0,0]
	v_pk_mul_f32 v[116:117], v[116:117], v[116:117]
	v_pk_mul_f32 v[118:119], v[118:119], v[118:119]
	v_max_f32_e32 v112, 0, v112
	v_max_f32_e32 v113, 0, v113
	v_max_f32_e32 v114, 0, v114
	v_max_f32_e32 v115, 0, v115
	v_max_f32_e32 v108, 0, v108
	v_max_f32_e32 v109, 0, v109
	v_max_f32_e32 v110, 0, v110
	v_max_f32_e32 v111, 0, v111
	v_max_f32_e32 v104, 0, v104
	v_max_f32_e32 v105, 0, v105
	v_max_f32_e32 v106, 0, v106
	v_max_f32_e32 v107, 0, v107
	v_cvt_pk_bf16_f32 v116, v116, v117
	v_cvt_pk_bf16_f32 v117, v118, v119
	v_lshl_add_u64 v[118:119], s[86:87], 0, v[120:121]
	v_pk_mul_f32 v[112:113], v[112:113], v[112:113]
	v_pk_mul_f32 v[114:115], v[114:115], v[114:115]
	v_pk_mul_f32 v[108:109], v[108:109], v[108:109]
	v_pk_mul_f32 v[110:111], v[110:111], v[110:111]
	v_pk_mul_f32 v[104:105], v[104:105], v[104:105]
	v_pk_mul_f32 v[106:107], v[106:107], v[106:107]
	v_lshl_add_u64 v[118:119], v[118:119], 0, v[164:165]
	v_cvt_pk_bf16_f32 v112, v112, v113
	v_cvt_pk_bf16_f32 v113, v114, v115
	v_cvt_pk_bf16_f32 v108, v108, v109
	v_cvt_pk_bf16_f32 v109, v110, v111
	v_cvt_pk_bf16_f32 v104, v104, v105
	v_cvt_pk_bf16_f32 v105, v106, v107
	global_store_dwordx2 v[118:119], v[116:117], off
	global_store_dwordx2 v[118:119], v[112:113], off offset:32
	global_store_dwordx2 v[118:119], v[108:109], off offset:256
	global_store_dwordx2 v[118:119], v[104:105], off offset:288
	ds_read_b64 v[106:107], v187 offset:256
	v_add_u32_e32 v104, s15, v179
	v_ashrrev_i32_e32 v105, 31, v104
	v_lshlrev_b64 v[104:105], 13, v[104:105]
	s_waitcnt lgkmcnt(0)
; __device__ __forceinline__ float bflo(unsigned w) { return __uint_as_float(w << 16); }
; __device__ __forceinline__ float bfhi(unsigned w) { return __uint_as_float(w & 0xffff0000u); }
;     __device__ __forceinline__ void apply(const RowInfo& ri, const ColInfo& ci, int row, int col, f32x4 a, f32x4 pv, float& s1, float& s2) const {
;         f32x4 v = (a - ci.a * ri.mu) * ri.rstd + ci.b;
; #pragma unroll
;         for (int j = 0; j < 4; ++j) { const float r = fmaxf(v[j], 0.f); v[j] = r * r; }
;         *(u32x2*)(hid + (size_t)row * DFF + col) = pack4(v);
; template <class Epi>
; __device__ __forceinline__ void gemm_phase(LAS unsigned char* lds, const bf16_t* Ag, const bf16_t* Btg, const int K, const int nM, const int nN, const Epi& E) {
;     ...
;             for (int gi = 0; gi < 8; ++gi) {
;                 const int ai = gi >> 2, m = gi & 3;
;                 const int lrow = ai * 128 + wr * 64 + m * 16 + fr, row = prow0(pm) + lrow;
;                 if (!Epi::PRELOAD && gi == 0) {
; #pragma unroll
;                     for (int g2 = 0; g2 < 4; ++g2)
; #pragma unroll
;                         for (int bj = 0; bj < 2; ++bj)
; #pragma unroll
;                             for (int n = 0; n < 2; ++n) pk[g2][bj][n] = (u32x2){0u, 0u};
;                 }
;                 if (Epi::PRELOAD && m == 0) {
; #pragma unroll
;                     for (int g2 = 0; g2 < 4; ++g2)
; #pragma unroll
;                         for (int bj = 0; bj < 2; ++bj)
; #pragma unroll
;                             for (int n = 0; n < 2; ++n) pk[g2][bj][n] = E.preload_pk(prow0(pm) + ai * 128 + wr * 64 + g2 * 16 + fr, pn * 256 + bj * 128 + wc * 32 + n * 16 + fq * 4);
;                 }
;                 f32x4 pv[2][2];
; #pragma unroll
;                 for (int bj = 0; bj < 2; ++bj)
; #pragma unroll
;                     for (int n = 0; n < 2; ++n) { const u32x2 w = pk[m][bj][n]; pv[bj][n] = (f32x4){bflo(w.x), bfhi(w.x), bflo(w.y), bfhi(w.y)}; }
;                 const RowInfo ri = E.rowinfo(row, lrow, par, lds);
;                 float s1 = 0.f, s2 = 0.f;
; #pragma unroll
;                 for (int bj = 0; bj < 2; ++bj)
; #pragma unroll
;                     for (int n = 0; n < 2; ++n) E.apply(ri, ci[bj][n], row, pn * 256 + bj * 128 + wc * 32 + n * 16 + fq * 4, acc[ai][bj][m][n], pv[bj][n], s1, s2);
	v_pk_fma_f32 v[102:103], v[150:151], v[106:107], v[102:103] op_sel_hi:[1,0,1]
	v_pk_fma_f32 v[100:101], v[148:149], v[106:107], v[100:101] op_sel_hi:[1,0,1] neg_lo:[1,0,0] neg_hi:[1,0,0]
	v_pk_fma_f32 v[102:103], v[106:107], v[102:103], v[158:159] op_sel:[1,0,0]
	v_pk_fma_f32 v[100:101], v[106:107], v[100:101], v[156:157] op_sel:[1,0,0]
	v_pk_fma_f32 v[98:99], v[138:139], v[106:107], v[98:99] op_sel_hi:[1,0,1]
	v_pk_fma_f32 v[96:97], v[136:137], v[106:107], v[96:97] op_sel_hi:[1,0,1] neg_lo:[1,0,0] neg_hi:[1,0,0]
	v_pk_fma_f32 v[94:95], v[130:131], v[106:107], v[94:95] op_sel_hi:[1,0,1]
	v_pk_fma_f32 v[92:93], v[128:129], v[106:107], v[92:93] op_sel_hi:[1,0,1] neg_lo:[1,0,0] neg_hi:[1,0,0]
	v_pk_fma_f32 v[90:91], v[126:127], v[106:107], v[90:91] op_sel_hi:[1,0,1]
	v_pk_fma_f32 v[88:89], v[124:125], v[106:107], v[88:89] op_sel_hi:[1,0,1] neg_lo:[1,0,0] neg_hi:[1,0,0]
	v_max_f32_e32 v100, 0, v100
	v_max_f32_e32 v101, 0, v101
	v_max_f32_e32 v102, 0, v102
	v_max_f32_e32 v103, 0, v103
	v_pk_fma_f32 v[98:99], v[106:107], v[98:99], v[142:143] op_sel:[1,0,0]
	v_pk_fma_f32 v[96:97], v[106:107], v[96:97], v[140:141] op_sel:[1,0,0]
	v_pk_fma_f32 v[94:95], v[106:107], v[94:95], v[134:135] op_sel:[1,0,0]
	v_pk_fma_f32 v[92:93], v[106:107], v[92:93], v[132:133] op_sel:[1,0,0]
	v_pk_fma_f32 v[90:91], v[106:107], v[90:91], v[154:155] op_sel:[1,0,0]
	v_pk_fma_f32 v[88:89], v[106:107], v[88:89], v[152:153] op_sel:[1,0,0]
	v_pk_mul_f32 v[100:101], v[100:101], v[100:101]
	v_pk_mul_f32 v[102:103], v[102:103], v[102:103]
	v_max_f32_e32 v96, 0, v96
	v_max_f32_e32 v97, 0, v97
	v_max_f32_e32 v98, 0, v98
	v_max_f32_e32 v99, 0, v99
	v_max_f32_e32 v92, 0, v92
	v_max_f32_e32 v93, 0, v93
	v_max_f32_e32 v94, 0, v94
	v_max_f32_e32 v95, 0, v95
	v_max_f32_e32 v88, 0, v88
	v_max_f32_e32 v89, 0, v89
	v_max_f32_e32 v90, 0, v90
	v_max_f32_e32 v91, 0, v91
	v_cvt_pk_bf16_f32 v100, v100, v101
	v_cvt_pk_bf16_f32 v101, v102, v103
	v_lshl_add_u64 v[102:103], s[86:87], 0, v[104:105]
	v_pk_mul_f32 v[96:97], v[96:97], v[96:97]
	v_pk_mul_f32 v[98:99], v[98:99], v[98:99]
	v_pk_mul_f32 v[92:93], v[92:93], v[92:93]
	v_pk_mul_f32 v[94:95], v[94:95], v[94:95]
	v_pk_mul_f32 v[88:89], v[88:89], v[88:89]
	v_pk_mul_f32 v[90:91], v[90:91], v[90:91]
	v_lshl_add_u64 v[102:103], v[102:103], 0, v[164:165]
	v_cvt_pk_bf16_f32 v96, v96, v97
	v_cvt_pk_bf16_f32 v97, v98, v99
	v_cvt_pk_bf16_f32 v92, v92, v93
	v_cvt_pk_bf16_f32 v93, v94, v95
	v_cvt_pk_bf16_f32 v88, v88, v89
	v_cvt_pk_bf16_f32 v89, v90, v91
	global_store_dwordx2 v[102:103], v[100:101], off
	global_store_dwordx2 v[102:103], v[96:97], off offset:32
	global_store_dwordx2 v[102:103], v[92:93], off offset:256
	global_store_dwordx2 v[102:103], v[88:89], off offset:288
	ds_read_b64 v[90:91], v187 offset:384
	v_add_u32_e32 v88, s15, v180
	v_ashrrev_i32_e32 v89, 31, v88
	v_lshlrev_b64 v[88:89], 13, v[88:89]
	s_waitcnt lgkmcnt(0)
	v_pk_fma_f32 v[86:87], v[150:151], v[90:91], v[86:87] op_sel_hi:[1,0,1]
	v_pk_fma_f32 v[84:85], v[148:149], v[90:91], v[84:85] op_sel_hi:[1,0,1] neg_lo:[1,0,0] neg_hi:[1,0,0]
	v_pk_fma_f32 v[86:87], v[90:91], v[86:87], v[158:159] op_sel:[1,0,0]
	v_pk_fma_f32 v[84:85], v[90:91], v[84:85], v[156:157] op_sel:[1,0,0]
	v_pk_fma_f32 v[82:83], v[138:139], v[90:91], v[82:83] op_sel_hi:[1,0,1]
	v_pk_fma_f32 v[80:81], v[136:137], v[90:91], v[80:81] op_sel_hi:[1,0,1] neg_lo:[1,0,0] neg_hi:[1,0,0]
	v_pk_fma_f32 v[78:79], v[130:131], v[90:91], v[78:79] op_sel_hi:[1,0,1]
	v_pk_fma_f32 v[76:77], v[128:129], v[90:91], v[76:77] op_sel_hi:[1,0,1] neg_lo:[1,0,0] neg_hi:[1,0,0]
	v_pk_fma_f32 v[74:75], v[126:127], v[90:91], v[74:75] op_sel_hi:[1,0,1]
	v_pk_fma_f32 v[72:73], v[124:125], v[90:91], v[72:73] op_sel_hi:[1,0,1] neg_lo:[1,0,0] neg_hi:[1,0,0]
	v_max_f32_e32 v84, 0, v84
	v_max_f32_e32 v85, 0, v85
	v_max_f32_e32 v86, 0, v86
	v_max_f32_e32 v87, 0, v87
	v_pk_fma_f32 v[82:83], v[90:91], v[82:83], v[142:143] op_sel:[1,0,0]
	v_pk_fma_f32 v[80:81], v[90:91], v[80:81], v[140:141] op_sel:[1,0,0]
	v_pk_fma_f32 v[78:79], v[90:91], v[78:79], v[134:135] op_sel:[1,0,0]
	v_pk_fma_f32 v[76:77], v[90:91], v[76:77], v[132:133] op_sel:[1,0,0]
	v_pk_fma_f32 v[74:75], v[90:91], v[74:75], v[154:155] op_sel:[1,0,0]
	v_pk_fma_f32 v[72:73], v[90:91], v[72:73], v[152:153] op_sel:[1,0,0]
	v_pk_mul_f32 v[84:85], v[84:85], v[84:85]
	v_pk_mul_f32 v[86:87], v[86:87], v[86:87]
	v_max_f32_e32 v80, 0, v80
	v_max_f32_e32 v81, 0, v81
	v_max_f32_e32 v82, 0, v82
	v_max_f32_e32 v83, 0, v83
	v_max_f32_e32 v76, 0, v76
	v_max_f32_e32 v77, 0, v77
	v_max_f32_e32 v78, 0, v78
	v_max_f32_e32 v79, 0, v79
	v_max_f32_e32 v72, 0, v72
	v_max_f32_e32 v73, 0, v73
	v_max_f32_e32 v74, 0, v74
	v_max_f32_e32 v75, 0, v75
	v_cvt_pk_bf16_f32 v84, v84, v85
	v_cvt_pk_bf16_f32 v85, v86, v87
	v_lshl_add_u64 v[86:87], s[86:87], 0, v[88:89]
	v_pk_mul_f32 v[80:81], v[80:81], v[80:81]
	v_pk_mul_f32 v[82:83], v[82:83], v[82:83]
	v_pk_mul_f32 v[76:77], v[76:77], v[76:77]
	v_pk_mul_f32 v[78:79], v[78:79], v[78:79]
	v_pk_mul_f32 v[72:73], v[72:73], v[72:73]
	v_pk_mul_f32 v[74:75], v[74:75], v[74:75]
	v_lshl_add_u64 v[86:87], v[86:87], 0, v[164:165]
	v_cvt_pk_bf16_f32 v80, v80, v81
	v_cvt_pk_bf16_f32 v81, v82, v83
	v_cvt_pk_bf16_f32 v76, v76, v77
	v_cvt_pk_bf16_f32 v77, v78, v79
	v_cvt_pk_bf16_f32 v72, v72, v73
	v_cvt_pk_bf16_f32 v73, v74, v75
	global_store_dwordx2 v[86:87], v[84:85], off
	global_store_dwordx2 v[86:87], v[80:81], off offset:32
	global_store_dwordx2 v[86:87], v[76:77], off offset:256
	global_store_dwordx2 v[86:87], v[72:73], off offset:288
	ds_read_b64 v[74:75], v187 offset:1024
	v_add_u32_e32 v72, s15, v181
	v_ashrrev_i32_e32 v73, 31, v72
	v_lshlrev_b64 v[72:73], 13, v[72:73]
	s_waitcnt lgkmcnt(0)
; __device__ __forceinline__ float bflo(unsigned w) { return __uint_as_float(w << 16); }
; __device__ __forceinline__ float bfhi(unsigned w) { return __uint_as_float(w & 0xffff0000u); }
;     __device__ __forceinline__ void apply(const RowInfo& ri, const ColInfo& ci, int row, int col, f32x4 a, f32x4 pv, float& s1, float& s2) const {
;         f32x4 v = (a - ci.a * ri.mu) * ri.rstd + ci.b;
; #pragma unroll
;         for (int j = 0; j < 4; ++j) { const float r = fmaxf(v[j], 0.f); v[j] = r * r; }
;         *(u32x2*)(hid + (size_t)row * DFF + col) = pack4(v);
; template <class Epi>
; __device__ __forceinline__ void gemm_phase(LAS unsigned char* lds, const bf16_t* Ag, const bf16_t* Btg, const int K, const int nM, const int nN, const Epi& E) {
;     ...
;             for (int gi = 0; gi < 8; ++gi) {
;                 const int ai = gi >> 2, m = gi & 3;
;                 const int lrow = ai * 128 + wr * 64 + m * 16 + fr, row = prow0(pm) + lrow;
;                 if (!Epi::PRELOAD && gi == 0) {
; #pragma unroll
;                     for (int g2 = 0; g2 < 4; ++g2)
; #pragma unroll
;                         for (int bj = 0; bj < 2; ++bj)
; #pragma unroll
;                             for (int n = 0; n < 2; ++n) pk[g2][bj][n] = (u32x2){0u, 0u};
;                 }
;                 if (Epi::PRELOAD && m == 0) {
; #pragma unroll
;                     for (int g2 = 0; g2 < 4; ++g2)
; #pragma unroll
;                         for (int bj = 0; bj < 2; ++bj)
; #pragma unroll
;                             for (int n = 0; n < 2; ++n) pk[g2][bj][n] = E.preload_pk(prow0(pm) + ai * 128 + wr * 64 + g2 * 16 + fr, pn * 256 + bj * 128 + wc * 32 + n * 16 + fq * 4);
;                 }
;                 f32x4 pv[2][2];
; #pragma unroll
;                 for (int bj = 0; bj < 2; ++bj)
; #pragma unroll
;                     for (int n = 0; n < 2; ++n) { const u32x2 w = pk[m][bj][n]; pv[bj][n] = (f32x4){bflo(w.x), bfhi(w.x), bflo(w.y), bfhi(w.y)}; }
;                 const RowInfo ri = E.rowinfo(row, lrow, par, lds);
;                 float s1 = 0.f, s2 = 0.f;
; #pragma unroll
;                 for (int bj = 0; bj < 2; ++bj)
; #pragma unroll
;                     for (int n = 0; n < 2; ++n) E.apply(ri, ci[bj][n], row, pn * 256 + bj * 128 + wc * 32 + n * 16 + fq * 4, acc[ai][bj][m][n], pv[bj][n], s1, s2);
	v_pk_fma_f32 v[62:63], v[150:151], v[74:75], v[62:63] op_sel_hi:[1,0,1]
	v_pk_fma_f32 v[60:61], v[148:149], v[74:75], v[60:61] op_sel_hi:[1,0,1] neg_lo:[1,0,0] neg_hi:[1,0,0]
	v_pk_fma_f32 v[62:63], v[74:75], v[62:63], v[158:159] op_sel:[1,0,0]
	v_pk_fma_f32 v[60:61], v[74:75], v[60:61], v[156:157] op_sel:[1,0,0]
	v_pk_fma_f32 v[58:59], v[138:139], v[74:75], v[58:59] op_sel_hi:[1,0,1]
	v_pk_fma_f32 v[56:57], v[136:137], v[74:75], v[56:57] op_sel_hi:[1,0,1] neg_lo:[1,0,0] neg_hi:[1,0,0]
	v_max_f32_e32 v60, 0, v60
	v_max_f32_e32 v61, 0, v61
	v_max_f32_e32 v62, 0, v62
	v_max_f32_e32 v63, 0, v63
	v_pk_fma_f32 v[58:59], v[74:75], v[58:59], v[142:143] op_sel:[1,0,0]
	v_pk_fma_f32 v[56:57], v[74:75], v[56:57], v[140:141] op_sel:[1,0,0]
	v_pk_mul_f32 v[60:61], v[60:61], v[60:61]
	v_pk_mul_f32 v[62:63], v[62:63], v[62:63]
	v_max_f32_e32 v56, 0, v56
	v_max_f32_e32 v57, 0, v57
	v_max_f32_e32 v58, 0, v58
	v_max_f32_e32 v59, 0, v59
	v_cvt_pk_bf16_f32 v60, v60, v61
	v_cvt_pk_bf16_f32 v61, v62, v63
	v_lshl_add_u64 v[62:63], s[86:87], 0, v[72:73]
	v_pk_mul_f32 v[56:57], v[56:57], v[56:57]
	v_pk_mul_f32 v[58:59], v[58:59], v[58:59]
	v_lshl_add_u64 v[62:63], v[62:63], 0, v[164:165]
	v_cvt_pk_bf16_f32 v56, v56, v57
	v_cvt_pk_bf16_f32 v57, v58, v59
	global_store_dwordx2 v[62:63], v[56:57], off offset:32
	v_pk_fma_f32 v[56:57], v[130:131], v[74:75], v[70:71] op_sel_hi:[1,0,1]
	v_pk_fma_f32 v[58:59], v[128:129], v[74:75], v[68:69] op_sel_hi:[1,0,1] neg_lo:[1,0,0] neg_hi:[1,0,0]
	v_pk_fma_f32 v[56:57], v[74:75], v[56:57], v[134:135] op_sel:[1,0,0]
	v_pk_fma_f32 v[58:59], v[74:75], v[58:59], v[132:133] op_sel:[1,0,0]
	v_max_f32_e32 v56, 0, v56
	v_max_f32_e32 v58, 0, v58
	v_max_f32_e32 v59, 0, v59
	v_max_f32_e32 v57, 0, v57
	v_pk_mul_f32 v[58:59], v[58:59], v[58:59]
	v_pk_mul_f32 v[56:57], v[56:57], v[56:57]
	v_cvt_pk_bf16_f32 v58, v58, v59
	v_cvt_pk_bf16_f32 v59, v56, v57
	global_store_dwordx2 v[62:63], v[58:59], off offset:256
	v_pk_fma_f32 v[56:57], v[126:127], v[74:75], v[66:67] op_sel_hi:[1,0,1]
	v_pk_fma_f32 v[58:59], v[124:125], v[74:75], v[64:65] op_sel_hi:[1,0,1] neg_lo:[1,0,0] neg_hi:[1,0,0]
	v_pk_fma_f32 v[56:57], v[74:75], v[56:57], v[154:155] op_sel:[1,0,0]
	v_pk_fma_f32 v[58:59], v[74:75], v[58:59], v[152:153] op_sel:[1,0,0]
	v_max_f32_e32 v56, 0, v56
	v_max_f32_e32 v58, 0, v58
	v_max_f32_e32 v59, 0, v59
	v_max_f32_e32 v57, 0, v57
	v_pk_mul_f32 v[58:59], v[58:59], v[58:59]
	v_pk_mul_f32 v[56:57], v[56:57], v[56:57]
	v_cvt_pk_bf16_f32 v58, v58, v59
	v_cvt_pk_bf16_f32 v59, v56, v57
	global_store_dwordx2 v[62:63], v[60:61], off
	global_store_dwordx2 v[62:63], v[58:59], off offset:288
	ds_read_b64 v[58:59], v187 offset:1152
	v_add_u32_e32 v56, s15, v182
	v_ashrrev_i32_e32 v57, 31, v56
	v_lshlrev_b64 v[56:57], 13, v[56:57]
	s_waitcnt lgkmcnt(0)
	v_pk_fma_f32 v[46:47], v[150:151], v[58:59], v[46:47] op_sel_hi:[1,0,1]
	v_pk_fma_f32 v[44:45], v[148:149], v[58:59], v[44:45] op_sel_hi:[1,0,1] neg_lo:[1,0,0] neg_hi:[1,0,0]
	v_pk_fma_f32 v[46:47], v[58:59], v[46:47], v[158:159] op_sel:[1,0,0]
	v_pk_fma_f32 v[44:45], v[58:59], v[44:45], v[156:157] op_sel:[1,0,0]
	v_pk_fma_f32 v[42:43], v[138:139], v[58:59], v[42:43] op_sel_hi:[1,0,1]
	v_pk_fma_f32 v[40:41], v[136:137], v[58:59], v[40:41] op_sel_hi:[1,0,1] neg_lo:[1,0,0] neg_hi:[1,0,0]
	v_max_f32_e32 v44, 0, v44
	v_max_f32_e32 v45, 0, v45
	v_max_f32_e32 v46, 0, v46
	v_max_f32_e32 v47, 0, v47
	v_pk_fma_f32 v[42:43], v[58:59], v[42:43], v[142:143] op_sel:[1,0,0]
	v_pk_fma_f32 v[40:41], v[58:59], v[40:41], v[140:141] op_sel:[1,0,0]
	v_pk_mul_f32 v[44:45], v[44:45], v[44:45]
	v_pk_mul_f32 v[46:47], v[46:47], v[46:47]
	v_max_f32_e32 v40, 0, v40
	v_max_f32_e32 v41, 0, v41
	v_max_f32_e32 v42, 0, v42
	v_max_f32_e32 v43, 0, v43
	v_cvt_pk_bf16_f32 v44, v44, v45
	v_cvt_pk_bf16_f32 v45, v46, v47
	v_lshl_add_u64 v[46:47], s[86:87], 0, v[56:57]
	v_pk_mul_f32 v[40:41], v[40:41], v[40:41]
	v_pk_mul_f32 v[42:43], v[42:43], v[42:43]
	v_lshl_add_u64 v[46:47], v[46:47], 0, v[164:165]
	v_cvt_pk_bf16_f32 v40, v40, v41
	v_cvt_pk_bf16_f32 v41, v42, v43
	global_store_dwordx2 v[46:47], v[40:41], off offset:32
	v_pk_fma_f32 v[40:41], v[130:131], v[58:59], v[54:55] op_sel_hi:[1,0,1]
	v_pk_fma_f32 v[42:43], v[128:129], v[58:59], v[52:53] op_sel_hi:[1,0,1] neg_lo:[1,0,0] neg_hi:[1,0,0]
	v_pk_fma_f32 v[40:41], v[58:59], v[40:41], v[134:135] op_sel:[1,0,0]
	v_pk_fma_f32 v[42:43], v[58:59], v[42:43], v[132:133] op_sel:[1,0,0]
	v_max_f32_e32 v40, 0, v40
	v_max_f32_e32 v42, 0, v42
	v_max_f32_e32 v43, 0, v43
	v_max_f32_e32 v41, 0, v41
	v_pk_mul_f32 v[42:43], v[42:43], v[42:43]
	v_pk_mul_f32 v[40:41], v[40:41], v[40:41]
	v_cvt_pk_bf16_f32 v42, v42, v43
	v_cvt_pk_bf16_f32 v43, v40, v41
	global_store_dwordx2 v[46:47], v[42:43], off offset:256
	v_pk_fma_f32 v[40:41], v[126:127], v[58:59], v[50:51] op_sel_hi:[1,0,1]
	v_pk_fma_f32 v[42:43], v[124:125], v[58:59], v[48:49] op_sel_hi:[1,0,1] neg_lo:[1,0,0] neg_hi:[1,0,0]
	v_pk_fma_f32 v[40:41], v[58:59], v[40:41], v[154:155] op_sel:[1,0,0]
	v_pk_fma_f32 v[42:43], v[58:59], v[42:43], v[152:153] op_sel:[1,0,0]
	v_max_f32_e32 v40, 0, v40
	v_max_f32_e32 v42, 0, v42
	v_max_f32_e32 v43, 0, v43
	v_max_f32_e32 v41, 0, v41
	v_pk_mul_f32 v[42:43], v[42:43], v[42:43]
	v_pk_mul_f32 v[40:41], v[40:41], v[40:41]
	v_cvt_pk_bf16_f32 v42, v42, v43
	v_cvt_pk_bf16_f32 v43, v40, v41
	global_store_dwordx2 v[46:47], v[44:45], off
	global_store_dwordx2 v[46:47], v[42:43], off offset:288
	ds_read_b64 v[42:43], v187 offset:1280
	v_add_u32_e32 v40, s15, v183
	v_ashrrev_i32_e32 v41, 31, v40
	v_lshlrev_b64 v[40:41], 13, v[40:41]
	s_waitcnt lgkmcnt(0)
; __device__ __forceinline__ u32x2 pack4(const f32x4 a) { u32x2 v; v.x = cvt_pk_bf16(a[0], a[1]); v.y = cvt_pk_bf16(a[2], a[3]); return v; }
;     __device__ __forceinline__ void apply(const RowInfo& ri, const ColInfo& ci, int row, int col, f32x4 a, f32x4 pv, float& s1, float& s2) const {
;         f32x4 v = (a - ci.a * ri.mu) * ri.rstd + ci.b;
; #pragma unroll
;         for (int j = 0; j < 4; ++j) { const float r = fmaxf(v[j], 0.f); v[j] = r * r; }
;         *(u32x2*)(hid + (size_t)row * DFF + col) = pack4(v);
; template <class Epi>
; __device__ __forceinline__ void gemm_phase(LAS unsigned char* lds, const bf16_t* Ag, const bf16_t* Btg, const int K, const int nM, const int nN, const Epi& E) {
;     ...
;         if (!has_next) break;
; #pragma unroll
;         for (int a = 0; a < 2; ++a)
; #pragma unroll
;             for (int b = 0; b < 2; ++b)
; #pragma unroll
;                 for (int m = 0; m < 4; ++m)
; #pragma unroll
;                     for (int n = 0; n < 2; ++n) acc[a][b][m][n] = (f32x4){0.f, 0.f, 0.f, 0.f};
;         if (pmn != pm) par ^= 1;
;         u = un; pm = pmn; pn = pnn; cA = nA; cB = nB;
	v_pk_fma_f32 v[30:31], v[150:151], v[42:43], v[30:31] op_sel_hi:[1,0,1]
	v_pk_fma_f32 v[28:29], v[148:149], v[42:43], v[28:29] op_sel_hi:[1,0,1] neg_lo:[1,0,0] neg_hi:[1,0,0]
	v_pk_fma_f32 v[30:31], v[42:43], v[30:31], v[158:159] op_sel:[1,0,0]
	v_pk_fma_f32 v[28:29], v[42:43], v[28:29], v[156:157] op_sel:[1,0,0]
	v_pk_fma_f32 v[26:27], v[138:139], v[42:43], v[26:27] op_sel_hi:[1,0,1]
	v_pk_fma_f32 v[24:25], v[136:137], v[42:43], v[24:25] op_sel_hi:[1,0,1] neg_lo:[1,0,0] neg_hi:[1,0,0]
	v_max_f32_e32 v28, 0, v28
	v_max_f32_e32 v29, 0, v29
	v_max_f32_e32 v30, 0, v30
	v_max_f32_e32 v31, 0, v31
	v_pk_fma_f32 v[26:27], v[42:43], v[26:27], v[142:143] op_sel:[1,0,0]
	v_pk_fma_f32 v[24:25], v[42:43], v[24:25], v[140:141] op_sel:[1,0,0]
	v_pk_mul_f32 v[28:29], v[28:29], v[28:29]
	v_pk_mul_f32 v[30:31], v[30:31], v[30:31]
	v_max_f32_e32 v24, 0, v24
	v_max_f32_e32 v25, 0, v25
	v_max_f32_e32 v26, 0, v26
	v_max_f32_e32 v27, 0, v27
	v_cvt_pk_bf16_f32 v28, v28, v29
	v_cvt_pk_bf16_f32 v29, v30, v31
	v_lshl_add_u64 v[30:31], s[86:87], 0, v[40:41]
	v_pk_mul_f32 v[24:25], v[24:25], v[24:25]
	v_pk_mul_f32 v[26:27], v[26:27], v[26:27]
	v_lshl_add_u64 v[30:31], v[30:31], 0, v[164:165]
	v_cvt_pk_bf16_f32 v24, v24, v25
	v_cvt_pk_bf16_f32 v25, v26, v27
	global_store_dwordx2 v[30:31], v[24:25], off offset:32
	v_pk_fma_f32 v[24:25], v[130:131], v[42:43], v[38:39] op_sel_hi:[1,0,1]
	v_pk_fma_f32 v[26:27], v[128:129], v[42:43], v[36:37] op_sel_hi:[1,0,1] neg_lo:[1,0,0] neg_hi:[1,0,0]
	v_pk_fma_f32 v[24:25], v[42:43], v[24:25], v[134:135] op_sel:[1,0,0]
	v_pk_fma_f32 v[26:27], v[42:43], v[26:27], v[132:133] op_sel:[1,0,0]
	v_max_f32_e32 v24, 0, v24
	v_max_f32_e32 v26, 0, v26
	v_max_f32_e32 v27, 0, v27
	v_max_f32_e32 v25, 0, v25
	v_pk_mul_f32 v[26:27], v[26:27], v[26:27]
	v_pk_mul_f32 v[24:25], v[24:25], v[24:25]
	v_cvt_pk_bf16_f32 v26, v26, v27
	v_cvt_pk_bf16_f32 v27, v24, v25
	global_store_dwordx2 v[30:31], v[26:27], off offset:256
	v_pk_fma_f32 v[24:25], v[126:127], v[42:43], v[34:35] op_sel_hi:[1,0,1]
	v_pk_fma_f32 v[26:27], v[124:125], v[42:43], v[32:33] op_sel_hi:[1,0,1] neg_lo:[1,0,0] neg_hi:[1,0,0]
	v_pk_fma_f32 v[24:25], v[42:43], v[24:25], v[154:155] op_sel:[1,0,0]
	v_pk_fma_f32 v[26:27], v[42:43], v[26:27], v[152:153] op_sel:[1,0,0]
	v_max_f32_e32 v24, 0, v24
	v_max_f32_e32 v26, 0, v26
	v_max_f32_e32 v27, 0, v27
	v_max_f32_e32 v25, 0, v25
	v_pk_mul_f32 v[26:27], v[26:27], v[26:27]
	v_pk_mul_f32 v[24:25], v[24:25], v[24:25]
	v_cvt_pk_bf16_f32 v26, v26, v27
	v_cvt_pk_bf16_f32 v27, v24, v25
	global_store_dwordx2 v[30:31], v[28:29], off
	global_store_dwordx2 v[30:31], v[26:27], off offset:288
	ds_read_b64 v[26:27], v187 offset:1408
	v_add_u32_e32 v24, s15, v184
	v_ashrrev_i32_e32 v25, 31, v24
	v_lshlrev_b64 v[24:25], 13, v[24:25]
	s_mov_b64 s[14:15], -1
	s_waitcnt lgkmcnt(0)
	v_pk_fma_f32 v[14:15], v[150:151], v[26:27], v[14:15] op_sel_hi:[1,0,1]
	v_pk_fma_f32 v[12:13], v[148:149], v[26:27], v[12:13] op_sel_hi:[1,0,1] neg_lo:[1,0,0] neg_hi:[1,0,0]
	v_pk_fma_f32 v[14:15], v[26:27], v[14:15], v[158:159] op_sel:[1,0,0]
	v_pk_fma_f32 v[12:13], v[26:27], v[12:13], v[156:157] op_sel:[1,0,0]
	v_pk_fma_f32 v[10:11], v[138:139], v[26:27], v[10:11] op_sel_hi:[1,0,1]
	v_pk_fma_f32 v[8:9], v[136:137], v[26:27], v[8:9] op_sel_hi:[1,0,1] neg_lo:[1,0,0] neg_hi:[1,0,0]
	v_max_f32_e32 v12, 0, v12
	v_max_f32_e32 v13, 0, v13
	v_max_f32_e32 v14, 0, v14
	v_max_f32_e32 v15, 0, v15
	v_pk_fma_f32 v[10:11], v[26:27], v[10:11], v[142:143] op_sel:[1,0,0]
	v_pk_fma_f32 v[8:9], v[26:27], v[8:9], v[140:141] op_sel:[1,0,0]
	v_pk_mul_f32 v[12:13], v[12:13], v[12:13]
	v_pk_mul_f32 v[14:15], v[14:15], v[14:15]
	v_max_f32_e32 v8, 0, v8
	v_max_f32_e32 v9, 0, v9
	v_max_f32_e32 v10, 0, v10
	v_max_f32_e32 v11, 0, v11
	v_cvt_pk_bf16_f32 v12, v12, v13
	v_cvt_pk_bf16_f32 v13, v14, v15
	v_lshl_add_u64 v[14:15], s[86:87], 0, v[24:25]
	v_pk_mul_f32 v[8:9], v[8:9], v[8:9]
	v_pk_mul_f32 v[10:11], v[10:11], v[10:11]
	v_lshl_add_u64 v[14:15], v[14:15], 0, v[164:165]
	v_cvt_pk_bf16_f32 v8, v8, v9
	v_cvt_pk_bf16_f32 v9, v10, v11
	global_store_dwordx2 v[14:15], v[8:9], off offset:32
	v_pk_fma_f32 v[8:9], v[130:131], v[26:27], v[22:23] op_sel_hi:[1,0,1]
	v_pk_fma_f32 v[10:11], v[128:129], v[26:27], v[20:21] op_sel_hi:[1,0,1] neg_lo:[1,0,0] neg_hi:[1,0,0]
	v_pk_fma_f32 v[8:9], v[26:27], v[8:9], v[134:135] op_sel:[1,0,0]
	v_pk_fma_f32 v[10:11], v[26:27], v[10:11], v[132:133] op_sel:[1,0,0]
	v_max_f32_e32 v8, 0, v8
	v_max_f32_e32 v10, 0, v10
	v_max_f32_e32 v11, 0, v11
	v_max_f32_e32 v9, 0, v9
	v_pk_mul_f32 v[10:11], v[10:11], v[10:11]
	v_pk_mul_f32 v[8:9], v[8:9], v[8:9]
	v_cvt_pk_bf16_f32 v10, v10, v11
	v_cvt_pk_bf16_f32 v11, v8, v9
	global_store_dwordx2 v[14:15], v[10:11], off offset:256
	v_pk_fma_f32 v[8:9], v[126:127], v[26:27], v[18:19] op_sel_hi:[1,0,1]
	v_pk_fma_f32 v[10:11], v[124:125], v[26:27], v[16:17] op_sel_hi:[1,0,1] neg_lo:[1,0,0] neg_hi:[1,0,0]
	v_pk_fma_f32 v[8:9], v[26:27], v[8:9], v[154:155] op_sel:[1,0,0]
	v_pk_fma_f32 v[10:11], v[26:27], v[10:11], v[152:153] op_sel:[1,0,0]
	v_max_f32_e32 v8, 0, v8
	v_max_f32_e32 v10, 0, v10
	v_max_f32_e32 v11, 0, v11
	v_max_f32_e32 v9, 0, v9
	v_pk_mul_f32 v[10:11], v[10:11], v[10:11]
	v_pk_mul_f32 v[8:9], v[8:9], v[8:9]
	v_cvt_pk_bf16_f32 v10, v10, v11
	v_cvt_pk_bf16_f32 v11, v8, v9
	global_store_dwordx2 v[14:15], v[12:13], off
	global_store_dwordx2 v[14:15], v[10:11], off offset:288
	s_cbranch_vccz .LBB0_71
	s_cmp_lg_u32 s67, s66
	s_cselect_b64 s[14:15], -1, 0
	v_cndmask_b32_e64 v8, 0, 1, s[14:15]
	s_mov_b64 s[14:15], 0
	v_readfirstlane_b32 s12, v8
	s_xor_b32 s64, s64, s12
	s_branch .LBB0_71
